# late-pass weight stores (full 128-B lines) written through with sc1 so SEAM(3) finds little dirty L2
# baseline (speedup 1.0000x reference)
.Lgv2_common:
	s_lshr_b32 s13, s12, s11
	s_lshl_b32 s15, s13, s11
	s_sub_i32 s14, s12, s15
	s_add_i32 s15, s10, 6
	s_lshl_b32 s15, s13, s15
	s_lshl_b32 s21, s14, 7
	s_add_i32 s15, s15, s21
	s_lshl_b32 s29, 8, s10
	v_lshlrev_b32_e32 v4, s10, v2
	v_lshl_add_u32 v4, v3, 4, v4
	s_lshl_b32 s21, s13, 8
	s_waitcnt lgkmcnt(0)
	s_add_u32 s4, s4, s71
	s_addc_u32 s5, s5, 0
	s_add_u32 s4, s4, s15
	s_addc_u32 s5, s5, 0
	s_add_u32 s6, s6, s72
	s_addc_u32 s7, s7, 0
	s_add_u32 s6, s6, s21
	s_addc_u32 s7, s7, 0
	s_add_u32 s8, s8, s72
	s_addc_u32 s9, s9, 0
	s_add_u32 s8, s8, s21
	s_addc_u32 s9, s9, 0
	global_load_dwordx4 v[132:135], v4, s[4:5] nt
	s_add_u32 s4, s4, s29
	s_addc_u32 s5, s5, 0
	global_load_dwordx4 v[136:139], v4, s[4:5] nt
	s_add_u32 s4, s4, s29
	s_addc_u32 s5, s5, 0
	global_load_dwordx4 v[140:143], v4, s[4:5] nt
	s_add_u32 s4, s4, s29
	s_addc_u32 s5, s5, 0
	global_load_dwordx4 v[144:147], v4, s[4:5] nt
	s_add_u32 s4, s4, s29
	s_addc_u32 s5, s5, 0
	global_load_dwordx4 v[148:151], v4, s[4:5] nt
	s_add_u32 s4, s4, s29
	s_addc_u32 s5, s5, 0
	global_load_dwordx4 v[152:155], v4, s[4:5] nt
	s_add_u32 s4, s4, s29
	s_addc_u32 s5, s5, 0
	global_load_dwordx4 v[156:159], v4, s[4:5] nt
	s_add_u32 s4, s4, s29
	s_addc_u32 s5, s5, 0
	global_load_dwordx4 v[160:163], v4, s[4:5] nt
	global_load_dword v208, v5, s[6:7]
	global_load_dword v209, v5, s[8:9]
	s_lshl_b32 s15, s14, 17
	s_lshl_b32 s21, s13, 7
	s_add_i32 s15, s15, s21
	s_add_u32 s42, s16, s69
	s_addc_u32 s43, s17, 0
	s_add_u32 s42, s42, s15
	s_addc_u32 s43, s43, 0
	s_lshl_b32 s15, s14, 7
	s_add_u32 s44, s16, s70
	s_addc_u32 s45, s17, 0
	s_add_u32 s44, s44, s15
	s_addc_u32 s45, s45, 0
	s_addk_i32 s30, 0x800
	s_waitcnt vmcnt(10)
	ds_write_b32 v10, v206
	ds_write_b32 v10, v207 offset:256
	ds_read_b128 v[210:213], v11
	ds_read_b128 v[214:217], v11 offset:16
	ds_read_b128 v[218:221], v11 offset:256
	ds_read_b128 v[222:225], v11 offset:272
	s_waitcnt lgkmcnt(0)
	v_mul_f32_e32 v226, v100, v218
	v_mul_f32_e32 v100, v100, v210
	v_mul_f32_e32 v227, v101, v218
	v_mul_f32_e32 v101, v101, v210
	v_mul_f32_e32 v228, v102, v218
	v_mul_f32_e32 v102, v102, v210
	v_mul_f32_e32 v229, v103, v218
	v_mul_f32_e32 v103, v103, v210
	v_fmac_f32_e32 v226, v104, v219
	v_mul_f32_e32 v104, v104, v211
	v_fmac_f32_e32 v227, v105, v219
	v_mul_f32_e32 v105, v105, v211
	v_fmac_f32_e32 v228, v106, v219
	v_mul_f32_e32 v106, v106, v211
	v_fmac_f32_e32 v229, v107, v219
	v_mul_f32_e32 v107, v107, v211
	v_fmac_f32_e32 v226, v108, v220
	v_mul_f32_e32 v108, v108, v212
	v_fmac_f32_e32 v227, v109, v220
	v_mul_f32_e32 v109, v109, v212
	v_fmac_f32_e32 v228, v110, v220
	v_mul_f32_e32 v110, v110, v212
	v_fmac_f32_e32 v229, v111, v220
	v_mul_f32_e32 v111, v111, v212
	v_fmac_f32_e32 v226, v112, v221
	v_mul_f32_e32 v112, v112, v213
	v_fmac_f32_e32 v227, v113, v221
	v_mul_f32_e32 v113, v113, v213
	v_fmac_f32_e32 v228, v114, v221
	v_mul_f32_e32 v114, v114, v213
	v_fmac_f32_e32 v229, v115, v221
	v_mul_f32_e32 v115, v115, v213
	v_fmac_f32_e32 v226, v116, v222
	v_mul_f32_e32 v116, v116, v214
	v_fmac_f32_e32 v227, v117, v222
	v_mul_f32_e32 v117, v117, v214
	v_fmac_f32_e32 v228, v118, v222
	v_mul_f32_e32 v118, v118, v214
	v_fmac_f32_e32 v229, v119, v222
	v_mul_f32_e32 v119, v119, v214
	v_fmac_f32_e32 v226, v120, v223
	v_mul_f32_e32 v120, v120, v215
	v_fmac_f32_e32 v227, v121, v223
	v_mul_f32_e32 v121, v121, v215
	v_fmac_f32_e32 v228, v122, v223
	v_mul_f32_e32 v122, v122, v215
	v_fmac_f32_e32 v229, v123, v223
	v_mul_f32_e32 v123, v123, v215
	v_fmac_f32_e32 v226, v124, v224
	v_mul_f32_e32 v124, v124, v216
	v_fmac_f32_e32 v227, v125, v224
	v_mul_f32_e32 v125, v125, v216
	v_fmac_f32_e32 v228, v126, v224
	v_mul_f32_e32 v126, v126, v216
	v_fmac_f32_e32 v229, v127, v224
	v_mul_f32_e32 v127, v127, v216
	v_fmac_f32_e32 v226, v128, v225
	v_mul_f32_e32 v128, v128, v217
	v_fmac_f32_e32 v227, v129, v225
	v_mul_f32_e32 v129, v129, v217
	v_fmac_f32_e32 v228, v130, v225
	v_mul_f32_e32 v130, v130, v217
	v_fmac_f32_e32 v229, v131, v225
	v_mul_f32_e32 v131, v131, v217
	ds_write_b128 v21, v[100:103]
	ds_write_b128 v22, v[104:107] offset:1024
	ds_write_b128 v23, v[108:111] offset:2048
	ds_write_b128 v24, v[112:115] offset:3072
	ds_write_b128 v25, v[116:119] offset:4096
	ds_write_b128 v26, v[120:123] offset:5120
	ds_write_b128 v27, v[124:127] offset:6144
	ds_write_b128 v28, v[128:131] offset:7168
	ds_read2_b32 v[100:101], v29 offset1:32
	ds_read2_b32 v[102:103], v29 offset0:64 offset1:96
	ds_read2_b32 v[104:105], v29 offset0:128 offset1:160
	ds_read2_b32 v[106:107], v29 offset0:192 offset1:224
	ds_read2_b32 v[108:109], v30 offset1:32
	ds_read2_b32 v[110:111], v30 offset0:64 offset1:96
	ds_read2_b32 v[112:113], v30 offset0:128 offset1:160
	ds_read2_b32 v[114:115], v30 offset0:192 offset1:224
	ds_read2_b32 v[116:117], v31 offset1:32
	ds_read2_b32 v[118:119], v31 offset0:64 offset1:96
	ds_read2_b32 v[120:121], v31 offset0:128 offset1:160
	ds_read2_b32 v[122:123], v31 offset0:192 offset1:224
	ds_read2_b32 v[124:125], v32 offset1:32
	ds_read2_b32 v[126:127], v32 offset0:64 offset1:96
	ds_read2_b32 v[128:129], v32 offset0:128 offset1:160
	ds_read2_b32 v[130:131], v32 offset0:192 offset1:224
	ds_bpermute_b32 v234, v12, v226
	ds_bpermute_b32 v235, v12, v227
	ds_bpermute_b32 v236, v12, v228
	ds_bpermute_b32 v237, v12, v229
	s_waitcnt lgkmcnt(4)
	v_cvt_pk_bf16_f32 v164, v100, v101
	v_cvt_pk_bf16_f32 v165, v102, v103
	v_cvt_pk_bf16_f32 v166, v104, v105
	v_cvt_pk_bf16_f32 v167, v106, v107
	v_cvt_pk_bf16_f32 v168, v108, v109
	v_cvt_pk_bf16_f32 v169, v110, v111
	v_cvt_pk_bf16_f32 v170, v112, v113
	v_cvt_pk_bf16_f32 v171, v114, v115
	v_cvt_pk_bf16_f32 v172, v116, v117
	v_cvt_pk_bf16_f32 v173, v118, v119
	v_cvt_pk_bf16_f32 v174, v120, v121
	v_cvt_pk_bf16_f32 v175, v122, v123
	v_cvt_pk_bf16_f32 v176, v124, v125
	v_cvt_pk_bf16_f32 v177, v126, v127
	v_cvt_pk_bf16_f32 v178, v128, v129
	v_cvt_pk_bf16_f32 v179, v130, v131
	s_waitcnt lgkmcnt(0)
	v_add_f32_e32 v226, v226, v234
	v_add_f32_e32 v227, v227, v235
	v_add_f32_e32 v228, v228, v236
	v_add_f32_e32 v229, v229, v237
	ds_bpermute_b32 v234, v13, v226
	ds_bpermute_b32 v235, v13, v227
	ds_bpermute_b32 v236, v13, v228
	ds_bpermute_b32 v237, v13, v229
	v_lshlrev_b32_e32 v238, 16, v164
	v_and_b32_e32 v239, s59, v164
	v_add_f32_e32 v230, v238, v239
	v_lshlrev_b32_e32 v238, 16, v165
	v_and_b32_e32 v239, s59, v165
	v_add_f32_e32 v230, v230, v238
	v_add_f32_e32 v230, v230, v239
	v_lshlrev_b32_e32 v238, 16, v166
	v_and_b32_e32 v239, s59, v166
	v_add_f32_e32 v230, v230, v238
	v_add_f32_e32 v230, v230, v239
	v_lshlrev_b32_e32 v238, 16, v167
	v_and_b32_e32 v239, s59, v167
	v_add_f32_e32 v230, v230, v238
	v_add_f32_e32 v230, v230, v239
	v_lshlrev_b32_e32 v238, 16, v168
	v_and_b32_e32 v239, s59, v168
	v_add_f32_e32 v231, v238, v239
	v_lshlrev_b32_e32 v238, 16, v169
	v_and_b32_e32 v239, s59, v169
	v_add_f32_e32 v231, v231, v238
	v_add_f32_e32 v231, v231, v239
	v_lshlrev_b32_e32 v238, 16, v170
	v_and_b32_e32 v239, s59, v170
	v_add_f32_e32 v231, v231, v238
	v_add_f32_e32 v231, v231, v239
	v_lshlrev_b32_e32 v238, 16, v171
	v_and_b32_e32 v239, s59, v171
	v_add_f32_e32 v231, v231, v238
	v_add_f32_e32 v231, v231, v239
	s_waitcnt lgkmcnt(0)
	v_add_f32_e32 v226, v226, v234
	v_add_f32_e32 v227, v227, v235
	v_add_f32_e32 v228, v228, v236
	v_add_f32_e32 v229, v229, v237
	ds_bpermute_b32 v234, v14, v226
	ds_bpermute_b32 v235, v14, v227
	ds_bpermute_b32 v236, v14, v228
	ds_bpermute_b32 v237, v14, v229
	v_lshlrev_b32_e32 v238, 16, v172
	v_and_b32_e32 v239, s59, v172
	v_add_f32_e32 v232, v238, v239
	v_lshlrev_b32_e32 v238, 16, v173
	v_and_b32_e32 v239, s59, v173
	v_add_f32_e32 v232, v232, v238
	v_add_f32_e32 v232, v232, v239
	v_lshlrev_b32_e32 v238, 16, v174
	v_and_b32_e32 v239, s59, v174
	v_add_f32_e32 v232, v232, v238
	v_add_f32_e32 v232, v232, v239
	v_lshlrev_b32_e32 v238, 16, v175
	v_and_b32_e32 v239, s59, v175
	v_add_f32_e32 v232, v232, v238
	v_add_f32_e32 v232, v232, v239
	v_lshlrev_b32_e32 v238, 16, v176
	v_and_b32_e32 v239, s59, v176
	v_add_f32_e32 v233, v238, v239
	v_lshlrev_b32_e32 v238, 16, v177
	v_and_b32_e32 v239, s59, v177
	v_add_f32_e32 v233, v233, v238
	v_add_f32_e32 v233, v233, v239
	v_lshlrev_b32_e32 v238, 16, v178
	v_and_b32_e32 v239, s59, v178
	v_add_f32_e32 v233, v233, v238
	v_add_f32_e32 v233, v233, v239
	v_lshlrev_b32_e32 v238, 16, v179
	v_and_b32_e32 v239, s59, v179
	v_add_f32_e32 v233, v233, v238
	v_add_f32_e32 v233, v233, v239
	s_nop 1
	v_add_f32_dpp v230, v230, v230 quad_perm:[1,0,3,2] row_mask:0xf bank_mask:0xf
	v_add_f32_dpp v231, v231, v231 quad_perm:[1,0,3,2] row_mask:0xf bank_mask:0xf
	v_add_f32_dpp v232, v232, v232 quad_perm:[1,0,3,2] row_mask:0xf bank_mask:0xf
	v_add_f32_dpp v233, v233, v233 quad_perm:[1,0,3,2] row_mask:0xf bank_mask:0xf
	v_add_f32_dpp v230, v230, v230 quad_perm:[2,3,0,1] row_mask:0xf bank_mask:0xf
	v_add_f32_dpp v231, v231, v231 quad_perm:[2,3,0,1] row_mask:0xf bank_mask:0xf
	v_add_f32_dpp v232, v232, v232 quad_perm:[2,3,0,1] row_mask:0xf bank_mask:0xf
	v_add_f32_dpp v233, v233, v233 quad_perm:[2,3,0,1] row_mask:0xf bank_mask:0xf
	v_add_f32_dpp v230, v230, v230 row_half_mirror row_mask:0xf bank_mask:0xf
	v_add_f32_dpp v231, v231, v231 row_half_mirror row_mask:0xf bank_mask:0xf
	v_add_f32_dpp v232, v232, v232 row_half_mirror row_mask:0xf bank_mask:0xf
	v_add_f32_dpp v233, v233, v233 row_half_mirror row_mask:0xf bank_mask:0xf
	s_waitcnt lgkmcnt(0)
	v_add_f32_e32 v226, v226, v234
	v_add_f32_e32 v227, v227, v235
	v_add_f32_e32 v228, v228, v236
	v_add_f32_e32 v229, v229, v237
	global_store_dwordx4 v17, v[164:167], s[36:37] sc1
	global_store_dwordx4 v18, v[168:171], s[36:37] sc1
	global_store_dwordx4 v19, v[172:175], s[36:37] sc1
	global_store_dwordx4 v20, v[176:179], s[36:37] sc1
	s_add_u32 s48, s38, s40
	s_addc_u32 s49, s39, 0
	s_mov_b64 exec, s[56:57]
	global_atomic_add_f32 v15, v230, s[38:39]
	global_atomic_add_f32 v15, v231, s[38:39] offset:32
	global_atomic_add_f32 v15, v232, s[38:39] offset:64
	global_atomic_add_f32 v15, v233, s[38:39] offset:96
	s_mov_b64 exec, s[64:65]
	global_atomic_add_f32 v16, v226, s[48:49]
	global_atomic_add_f32 v16, v227, s[48:49] offset:4
	global_atomic_add_f32 v16, v228, s[48:49] offset:8
	global_atomic_add_f32 v16, v229, s[48:49] offset:12
	s_mov_b64 exec, -1
	s_cmp_lt_u32 s30, 0x4000
	s_cbranch_scc1 .Lgv3_w1
	s_cmp_lt_u32 s30, 0x5000
	s_cbranch_scc1 .Lgv3_pg
	s_cmp_lt_u32 s30, 0x5800
	s_cbranch_scc1 .Lgv3_wq
	s_cmp_lt_u32 s30, 0x5a00
	s_cbranch_scc1 .Lgv3_wk
	s_cmp_lt_u32 s30, 0x5c00
	s_cbranch_scc1 .Lgv3_wv
	s_mov_b32 s12, 0
	s_load_dwordx2 s[4:5], s[18:19], 0x98
	s_load_dwordx2 s[6:7], s[18:19], 0x100
	s_load_dwordx2 s[8:9], s[18:19], 0x108
	s_mov_b32 s10, 11
	s_mov_b32 s11, 4
	s_mov_b32 s69, 0x2d200000
	s_mov_b32 s70, 0x2e200000
	s_mov_b32 s40, 0x3000
	s_mov_b32 s71, 0
	s_mov_b32 s72, 0
	s_branch .Lgv3_common

.Lgv_loop:
	s_waitcnt vmcnt(22)
	ds_write_b32 v10, v208
	ds_write_b32 v10, v209 offset:256
	ds_read_b128 v[210:213], v11
	ds_read_b128 v[214:217], v11 offset:16
	ds_read_b128 v[218:221], v11 offset:256
	ds_read_b128 v[222:225], v11 offset:272
	s_waitcnt lgkmcnt(0)
	v_mul_f32_e32 v226, v132, v218
	v_mul_f32_e32 v132, v132, v210
	v_mul_f32_e32 v227, v133, v218
	v_mul_f32_e32 v133, v133, v210
	v_mul_f32_e32 v228, v134, v218
	v_mul_f32_e32 v134, v134, v210
	v_mul_f32_e32 v229, v135, v218
	v_mul_f32_e32 v135, v135, v210
	v_fmac_f32_e32 v226, v136, v219
	v_mul_f32_e32 v136, v136, v211
	v_fmac_f32_e32 v227, v137, v219
	v_mul_f32_e32 v137, v137, v211
	v_fmac_f32_e32 v228, v138, v219
	v_mul_f32_e32 v138, v138, v211
	v_fmac_f32_e32 v229, v139, v219
	v_mul_f32_e32 v139, v139, v211
	v_fmac_f32_e32 v226, v140, v220
	v_mul_f32_e32 v140, v140, v212
	v_fmac_f32_e32 v227, v141, v220
	v_mul_f32_e32 v141, v141, v212
	v_fmac_f32_e32 v228, v142, v220
	v_mul_f32_e32 v142, v142, v212
	v_fmac_f32_e32 v229, v143, v220
	v_mul_f32_e32 v143, v143, v212
	v_fmac_f32_e32 v226, v144, v221
	v_mul_f32_e32 v144, v144, v213
	v_fmac_f32_e32 v227, v145, v221
	v_mul_f32_e32 v145, v145, v213
	v_fmac_f32_e32 v228, v146, v221
	v_mul_f32_e32 v146, v146, v213
	v_fmac_f32_e32 v229, v147, v221
	v_mul_f32_e32 v147, v147, v213
	v_fmac_f32_e32 v226, v148, v222
	v_mul_f32_e32 v148, v148, v214
	v_fmac_f32_e32 v227, v149, v222
	v_mul_f32_e32 v149, v149, v214
	v_fmac_f32_e32 v228, v150, v222
	v_mul_f32_e32 v150, v150, v214
	v_fmac_f32_e32 v229, v151, v222
	v_mul_f32_e32 v151, v151, v214
	v_fmac_f32_e32 v226, v152, v223
	v_mul_f32_e32 v152, v152, v215
	v_fmac_f32_e32 v227, v153, v223
	v_mul_f32_e32 v153, v153, v215
	v_fmac_f32_e32 v228, v154, v223
	v_mul_f32_e32 v154, v154, v215
	v_fmac_f32_e32 v229, v155, v223
	v_mul_f32_e32 v155, v155, v215
	v_fmac_f32_e32 v226, v156, v224
	v_mul_f32_e32 v156, v156, v216
	v_fmac_f32_e32 v227, v157, v224
	v_mul_f32_e32 v157, v157, v216
	v_fmac_f32_e32 v228, v158, v224
	v_mul_f32_e32 v158, v158, v216
	v_fmac_f32_e32 v229, v159, v224
	v_mul_f32_e32 v159, v159, v216
	v_fmac_f32_e32 v226, v160, v225
	v_mul_f32_e32 v160, v160, v217
	v_fmac_f32_e32 v227, v161, v225
	v_mul_f32_e32 v161, v161, v217
	v_fmac_f32_e32 v228, v162, v225
	v_mul_f32_e32 v162, v162, v217
	v_fmac_f32_e32 v229, v163, v225
	v_mul_f32_e32 v163, v163, v217
	ds_write_b128 v21, v[132:135]
	ds_write_b128 v22, v[136:139] offset:1024
	ds_write_b128 v23, v[140:143] offset:2048
	ds_write_b128 v24, v[144:147] offset:3072
	ds_write_b128 v25, v[148:151] offset:4096
	ds_write_b128 v26, v[152:155] offset:5120
	ds_write_b128 v27, v[156:159] offset:6144
	ds_write_b128 v28, v[160:163] offset:7168
	ds_read2_b32 v[132:133], v29 offset1:32
	ds_read2_b32 v[134:135], v29 offset0:64 offset1:96
	ds_read2_b32 v[136:137], v29 offset0:128 offset1:160
	ds_read2_b32 v[138:139], v29 offset0:192 offset1:224
	ds_read2_b32 v[140:141], v30 offset1:32
	ds_read2_b32 v[142:143], v30 offset0:64 offset1:96
	ds_read2_b32 v[144:145], v30 offset0:128 offset1:160
	ds_read2_b32 v[146:147], v30 offset0:192 offset1:224
	ds_read2_b32 v[148:149], v31 offset1:32
	ds_read2_b32 v[150:151], v31 offset0:64 offset1:96
	ds_read2_b32 v[152:153], v31 offset0:128 offset1:160
	ds_read2_b32 v[154:155], v31 offset0:192 offset1:224
	ds_read2_b32 v[156:157], v32 offset1:32
	ds_read2_b32 v[158:159], v32 offset0:64 offset1:96
	ds_read2_b32 v[160:161], v32 offset0:128 offset1:160
	ds_read2_b32 v[162:163], v32 offset0:192 offset1:224
	ds_bpermute_b32 v234, v12, v226
	ds_bpermute_b32 v235, v12, v227
	ds_bpermute_b32 v236, v12, v228
	ds_bpermute_b32 v237, v12, v229
	s_waitcnt lgkmcnt(4)
	v_cvt_pk_bf16_f32 v190, v132, v133
	v_cvt_pk_bf16_f32 v191, v134, v135
	v_cvt_pk_bf16_f32 v192, v136, v137
	v_cvt_pk_bf16_f32 v193, v138, v139
	v_cvt_pk_bf16_f32 v194, v140, v141
	v_cvt_pk_bf16_f32 v195, v142, v143
	v_cvt_pk_bf16_f32 v196, v144, v145
	v_cvt_pk_bf16_f32 v197, v146, v147
	v_cvt_pk_bf16_f32 v198, v148, v149
	v_cvt_pk_bf16_f32 v199, v150, v151
	v_cvt_pk_bf16_f32 v200, v152, v153
	v_cvt_pk_bf16_f32 v201, v154, v155
	v_cvt_pk_bf16_f32 v202, v156, v157
	v_cvt_pk_bf16_f32 v203, v158, v159
	v_cvt_pk_bf16_f32 v204, v160, v161
	v_cvt_pk_bf16_f32 v205, v162, v163
	s_waitcnt lgkmcnt(0)
	v_add_f32_e32 v226, v226, v234
	v_add_f32_e32 v227, v227, v235
	v_add_f32_e32 v228, v228, v236
	v_add_f32_e32 v229, v229, v237
	ds_bpermute_b32 v234, v13, v226
	ds_bpermute_b32 v235, v13, v227
	ds_bpermute_b32 v236, v13, v228
	ds_bpermute_b32 v237, v13, v229
	v_lshlrev_b32_e32 v238, 16, v190
	v_and_b32_e32 v239, s59, v190
	v_add_f32_e32 v230, v238, v239
	v_lshlrev_b32_e32 v238, 16, v191
	v_and_b32_e32 v239, s59, v191
	v_add_f32_e32 v230, v230, v238
	v_add_f32_e32 v230, v230, v239
	v_lshlrev_b32_e32 v238, 16, v192
	v_and_b32_e32 v239, s59, v192
	v_add_f32_e32 v230, v230, v238
	v_add_f32_e32 v230, v230, v239
	v_lshlrev_b32_e32 v238, 16, v193
	v_and_b32_e32 v239, s59, v193
	v_add_f32_e32 v230, v230, v238
	v_add_f32_e32 v230, v230, v239
	v_lshlrev_b32_e32 v238, 16, v194
	v_and_b32_e32 v239, s59, v194
	v_add_f32_e32 v231, v238, v239
	v_lshlrev_b32_e32 v238, 16, v195
	v_and_b32_e32 v239, s59, v195
	v_add_f32_e32 v231, v231, v238
	v_add_f32_e32 v231, v231, v239
	v_lshlrev_b32_e32 v238, 16, v196
	v_and_b32_e32 v239, s59, v196
	v_add_f32_e32 v231, v231, v238
	v_add_f32_e32 v231, v231, v239
	v_lshlrev_b32_e32 v238, 16, v197
	v_and_b32_e32 v239, s59, v197
	v_add_f32_e32 v231, v231, v238
	v_add_f32_e32 v231, v231, v239
	s_waitcnt lgkmcnt(0)
	v_add_f32_e32 v226, v226, v234
	v_add_f32_e32 v227, v227, v235
	v_add_f32_e32 v228, v228, v236
	v_add_f32_e32 v229, v229, v237
	ds_bpermute_b32 v234, v14, v226
	ds_bpermute_b32 v235, v14, v227
	ds_bpermute_b32 v236, v14, v228
	ds_bpermute_b32 v237, v14, v229
	v_lshlrev_b32_e32 v238, 16, v198
	v_and_b32_e32 v239, s59, v198
	v_add_f32_e32 v232, v238, v239
	v_lshlrev_b32_e32 v238, 16, v199
	v_and_b32_e32 v239, s59, v199
	v_add_f32_e32 v232, v232, v238
	v_add_f32_e32 v232, v232, v239
	v_lshlrev_b32_e32 v238, 16, v200
	v_and_b32_e32 v239, s59, v200
	v_add_f32_e32 v232, v232, v238
	v_add_f32_e32 v232, v232, v239
	v_lshlrev_b32_e32 v238, 16, v201
	v_and_b32_e32 v239, s59, v201
	v_add_f32_e32 v232, v232, v238
	v_add_f32_e32 v232, v232, v239
	v_lshlrev_b32_e32 v238, 16, v202
	v_and_b32_e32 v239, s59, v202
	v_add_f32_e32 v233, v238, v239
	v_lshlrev_b32_e32 v238, 16, v203
	v_and_b32_e32 v239, s59, v203
	v_add_f32_e32 v233, v233, v238
	v_add_f32_e32 v233, v233, v239
	v_lshlrev_b32_e32 v238, 16, v204
	v_and_b32_e32 v239, s59, v204
	v_add_f32_e32 v233, v233, v238
	v_add_f32_e32 v233, v233, v239
	v_lshlrev_b32_e32 v238, 16, v205
	v_and_b32_e32 v239, s59, v205
	v_add_f32_e32 v233, v233, v238
	v_add_f32_e32 v233, v233, v239
	s_nop 1
	v_add_f32_dpp v230, v230, v230 quad_perm:[1,0,3,2] row_mask:0xf bank_mask:0xf
	v_add_f32_dpp v231, v231, v231 quad_perm:[1,0,3,2] row_mask:0xf bank_mask:0xf
	v_add_f32_dpp v232, v232, v232 quad_perm:[1,0,3,2] row_mask:0xf bank_mask:0xf
	v_add_f32_dpp v233, v233, v233 quad_perm:[1,0,3,2] row_mask:0xf bank_mask:0xf
	v_add_f32_dpp v230, v230, v230 quad_perm:[2,3,0,1] row_mask:0xf bank_mask:0xf
	v_add_f32_dpp v231, v231, v231 quad_perm:[2,3,0,1] row_mask:0xf bank_mask:0xf
	v_add_f32_dpp v232, v232, v232 quad_perm:[2,3,0,1] row_mask:0xf bank_mask:0xf
	v_add_f32_dpp v233, v233, v233 quad_perm:[2,3,0,1] row_mask:0xf bank_mask:0xf
	v_add_f32_dpp v230, v230, v230 row_half_mirror row_mask:0xf bank_mask:0xf
	v_add_f32_dpp v231, v231, v231 row_half_mirror row_mask:0xf bank_mask:0xf
	v_add_f32_dpp v232, v232, v232 row_half_mirror row_mask:0xf bank_mask:0xf
	v_add_f32_dpp v233, v233, v233 row_half_mirror row_mask:0xf bank_mask:0xf
	s_waitcnt lgkmcnt(0)
	v_add_f32_e32 v226, v226, v234
	v_add_f32_e32 v227, v227, v235
	v_add_f32_e32 v228, v228, v236
	v_add_f32_e32 v229, v229, v237
	global_store_dwordx4 v17, v[190:193], s[42:43] sc1
	global_store_dwordx4 v18, v[194:197], s[42:43] sc1
	global_store_dwordx4 v19, v[198:201], s[42:43] sc1
	global_store_dwordx4 v20, v[202:205], s[42:43] sc1
	s_add_u32 s48, s44, s47
	s_addc_u32 s49, s45, 0
	s_mov_b64 exec, s[56:57]
	global_atomic_add_f32 v15, v230, s[44:45]
	global_atomic_add_f32 v15, v231, s[44:45] offset:32
	global_atomic_add_f32 v15, v232, s[44:45] offset:64
	global_atomic_add_f32 v15, v233, s[44:45] offset:96
	s_mov_b64 exec, s[64:65]
	global_atomic_add_f32 v16, v226, s[48:49]
	global_atomic_add_f32 v16, v227, s[48:49] offset:4
	global_atomic_add_f32 v16, v228, s[48:49] offset:8
	global_atomic_add_f32 v16, v229, s[48:49] offset:12
	s_mov_b64 exec, -1
	s_cmp_lt_u32 s30, 0x4000
	s_cbranch_scc1 .Lgv4_w1
	s_cmp_lt_u32 s30, 0x5000
	s_cbranch_scc1 .Lgv4_pg
	s_cmp_lt_u32 s30, 0x5800
	s_cbranch_scc1 .Lgv4_wq
	s_cmp_lt_u32 s30, 0x5a00
	s_cbranch_scc1 .Lgv4_wk
	s_cmp_lt_u32 s30, 0x5c00
	s_cbranch_scc1 .Lgv4_wv
	s_mov_b32 s12, 0
	s_load_dwordx2 s[4:5], s[18:19], 0x98
	s_load_dwordx2 s[6:7], s[18:19], 0x100
	s_load_dwordx2 s[8:9], s[18:19], 0x108
	s_mov_b32 s10, 11
	s_mov_b32 s11, 4
	s_mov_b32 s69, 0x2d200000
	s_mov_b32 s70, 0x2e200000
	s_mov_b32 s47, 0x3000
	s_mov_b32 s71, 0
	s_mov_b32 s72, 0
	s_branch .Lgv4_common

.Lgv4_common:
	s_lshr_b32 s13, s12, s11
	s_lshl_b32 s15, s13, s11
	s_sub_i32 s14, s12, s15
	s_add_i32 s15, s10, 6
	s_lshl_b32 s15, s13, s15
	s_lshl_b32 s21, s14, 7
	s_add_i32 s15, s15, s21
	s_lshl_b32 s29, 8, s10
	v_lshlrev_b32_e32 v4, s10, v2
	v_lshl_add_u32 v4, v3, 4, v4
	s_lshl_b32 s21, s13, 8
	s_waitcnt lgkmcnt(0)
	s_add_u32 s4, s4, s71
	s_addc_u32 s5, s5, 0
	s_add_u32 s4, s4, s15
	s_addc_u32 s5, s5, 0
	s_add_u32 s6, s6, s72
	s_addc_u32 s7, s7, 0
	s_add_u32 s6, s6, s21
	s_addc_u32 s7, s7, 0
	s_add_u32 s8, s8, s72
	s_addc_u32 s9, s9, 0
	s_add_u32 s8, s8, s21
	s_addc_u32 s9, s9, 0
	global_load_dwordx4 v[132:135], v4, s[4:5] nt
	s_add_u32 s4, s4, s29
	s_addc_u32 s5, s5, 0
	global_load_dwordx4 v[136:139], v4, s[4:5] nt
	s_add_u32 s4, s4, s29
	s_addc_u32 s5, s5, 0
	global_load_dwordx4 v[140:143], v4, s[4:5] nt
	s_add_u32 s4, s4, s29
	s_addc_u32 s5, s5, 0
	global_load_dwordx4 v[144:147], v4, s[4:5] nt
	s_add_u32 s4, s4, s29
	s_addc_u32 s5, s5, 0
	global_load_dwordx4 v[148:151], v4, s[4:5] nt
	s_add_u32 s4, s4, s29
	s_addc_u32 s5, s5, 0
	global_load_dwordx4 v[152:155], v4, s[4:5] nt
	s_add_u32 s4, s4, s29
	s_addc_u32 s5, s5, 0
	global_load_dwordx4 v[156:159], v4, s[4:5] nt
	s_add_u32 s4, s4, s29
	s_addc_u32 s5, s5, 0
	global_load_dwordx4 v[160:163], v4, s[4:5] nt
	global_load_dword v208, v5, s[6:7]
	global_load_dword v209, v5, s[8:9]
	s_lshl_b32 s15, s14, 17
	s_lshl_b32 s21, s13, 7
	s_add_i32 s15, s15, s21
	s_add_u32 s42, s16, s69
	s_addc_u32 s43, s17, 0
	s_add_u32 s42, s42, s15
	s_addc_u32 s43, s43, 0
	s_lshl_b32 s15, s14, 7
	s_add_u32 s44, s16, s70
	s_addc_u32 s45, s17, 0
	s_add_u32 s44, s44, s15
	s_addc_u32 s45, s45, 0
	s_addk_i32 s30, 0x800
	s_waitcnt vmcnt(22)
	ds_write_b32 v10, v206
	ds_write_b32 v10, v207 offset:256
	ds_read_b128 v[210:213], v11
	ds_read_b128 v[214:217], v11 offset:16
	ds_read_b128 v[218:221], v11 offset:256
	ds_read_b128 v[222:225], v11 offset:272
	s_waitcnt lgkmcnt(0)
	v_mul_f32_e32 v226, v100, v218
	v_mul_f32_e32 v100, v100, v210
	v_mul_f32_e32 v227, v101, v218
	v_mul_f32_e32 v101, v101, v210
	v_mul_f32_e32 v228, v102, v218
	v_mul_f32_e32 v102, v102, v210
	v_mul_f32_e32 v229, v103, v218
	v_mul_f32_e32 v103, v103, v210
	v_fmac_f32_e32 v226, v104, v219
	v_mul_f32_e32 v104, v104, v211
	v_fmac_f32_e32 v227, v105, v219
	v_mul_f32_e32 v105, v105, v211
	v_fmac_f32_e32 v228, v106, v219
	v_mul_f32_e32 v106, v106, v211
	v_fmac_f32_e32 v229, v107, v219
	v_mul_f32_e32 v107, v107, v211
	v_fmac_f32_e32 v226, v108, v220
	v_mul_f32_e32 v108, v108, v212
	v_fmac_f32_e32 v227, v109, v220
	v_mul_f32_e32 v109, v109, v212
	v_fmac_f32_e32 v228, v110, v220
	v_mul_f32_e32 v110, v110, v212
	v_fmac_f32_e32 v229, v111, v220
	v_mul_f32_e32 v111, v111, v212
	v_fmac_f32_e32 v226, v112, v221
	v_mul_f32_e32 v112, v112, v213
	v_fmac_f32_e32 v227, v113, v221
	v_mul_f32_e32 v113, v113, v213
	v_fmac_f32_e32 v228, v114, v221
	v_mul_f32_e32 v114, v114, v213
	v_fmac_f32_e32 v229, v115, v221
	v_mul_f32_e32 v115, v115, v213
	v_fmac_f32_e32 v226, v116, v222
	v_mul_f32_e32 v116, v116, v214
	v_fmac_f32_e32 v227, v117, v222
	v_mul_f32_e32 v117, v117, v214
	v_fmac_f32_e32 v228, v118, v222
	v_mul_f32_e32 v118, v118, v214
	v_fmac_f32_e32 v229, v119, v222
	v_mul_f32_e32 v119, v119, v214
	v_fmac_f32_e32 v226, v120, v223
	v_mul_f32_e32 v120, v120, v215
	v_fmac_f32_e32 v227, v121, v223
	v_mul_f32_e32 v121, v121, v215
	v_fmac_f32_e32 v228, v122, v223
	v_mul_f32_e32 v122, v122, v215
	v_fmac_f32_e32 v229, v123, v223
	v_mul_f32_e32 v123, v123, v215
	v_fmac_f32_e32 v226, v124, v224
	v_mul_f32_e32 v124, v124, v216
	v_fmac_f32_e32 v227, v125, v224
	v_mul_f32_e32 v125, v125, v216
	v_fmac_f32_e32 v228, v126, v224
	v_mul_f32_e32 v126, v126, v216
	v_fmac_f32_e32 v229, v127, v224
	v_mul_f32_e32 v127, v127, v216
	v_fmac_f32_e32 v226, v128, v225
	v_mul_f32_e32 v128, v128, v217
	v_fmac_f32_e32 v227, v129, v225
	v_mul_f32_e32 v129, v129, v217
	v_fmac_f32_e32 v228, v130, v225
	v_mul_f32_e32 v130, v130, v217
	v_fmac_f32_e32 v229, v131, v225
	v_mul_f32_e32 v131, v131, v217
	ds_write_b128 v21, v[100:103]
	ds_write_b128 v22, v[104:107] offset:1024
	ds_write_b128 v23, v[108:111] offset:2048
	ds_write_b128 v24, v[112:115] offset:3072
	ds_write_b128 v25, v[116:119] offset:4096
	ds_write_b128 v26, v[120:123] offset:5120
	ds_write_b128 v27, v[124:127] offset:6144
	ds_write_b128 v28, v[128:131] offset:7168
	ds_read2_b32 v[100:101], v29 offset1:32
	ds_read2_b32 v[102:103], v29 offset0:64 offset1:96
	ds_read2_b32 v[104:105], v29 offset0:128 offset1:160
	ds_read2_b32 v[106:107], v29 offset0:192 offset1:224
	ds_read2_b32 v[108:109], v30 offset1:32
	ds_read2_b32 v[110:111], v30 offset0:64 offset1:96
	ds_read2_b32 v[112:113], v30 offset0:128 offset1:160
	ds_read2_b32 v[114:115], v30 offset0:192 offset1:224
	ds_read2_b32 v[116:117], v31 offset1:32
	ds_read2_b32 v[118:119], v31 offset0:64 offset1:96
	ds_read2_b32 v[120:121], v31 offset0:128 offset1:160
	ds_read2_b32 v[122:123], v31 offset0:192 offset1:224
	ds_read2_b32 v[124:125], v32 offset1:32
	ds_read2_b32 v[126:127], v32 offset0:64 offset1:96
	ds_read2_b32 v[128:129], v32 offset0:128 offset1:160
	ds_read2_b32 v[130:131], v32 offset0:192 offset1:224
	ds_bpermute_b32 v234, v12, v226
	ds_bpermute_b32 v235, v12, v227
	ds_bpermute_b32 v236, v12, v228
	ds_bpermute_b32 v237, v12, v229
	s_waitcnt lgkmcnt(4)
	v_cvt_pk_bf16_f32 v164, v100, v101
	v_cvt_pk_bf16_f32 v165, v102, v103
	v_cvt_pk_bf16_f32 v166, v104, v105
	v_cvt_pk_bf16_f32 v167, v106, v107
	v_cvt_pk_bf16_f32 v168, v108, v109
	v_cvt_pk_bf16_f32 v169, v110, v111
	v_cvt_pk_bf16_f32 v170, v112, v113
	v_cvt_pk_bf16_f32 v171, v114, v115
	v_cvt_pk_bf16_f32 v172, v116, v117
	v_cvt_pk_bf16_f32 v173, v118, v119
	v_cvt_pk_bf16_f32 v174, v120, v121
	v_cvt_pk_bf16_f32 v175, v122, v123
	v_cvt_pk_bf16_f32 v176, v124, v125
	v_cvt_pk_bf16_f32 v177, v126, v127
	v_cvt_pk_bf16_f32 v178, v128, v129
	v_cvt_pk_bf16_f32 v179, v130, v131
	s_waitcnt lgkmcnt(0)
	v_add_f32_e32 v226, v226, v234
	v_add_f32_e32 v227, v227, v235
	v_add_f32_e32 v228, v228, v236
	v_add_f32_e32 v229, v229, v237
	ds_bpermute_b32 v234, v13, v226
	ds_bpermute_b32 v235, v13, v227
	ds_bpermute_b32 v236, v13, v228
	ds_bpermute_b32 v237, v13, v229
	v_lshlrev_b32_e32 v238, 16, v164
	v_and_b32_e32 v239, s59, v164
	v_add_f32_e32 v230, v238, v239
	v_lshlrev_b32_e32 v238, 16, v165
	v_and_b32_e32 v239, s59, v165
	v_add_f32_e32 v230, v230, v238
	v_add_f32_e32 v230, v230, v239
	v_lshlrev_b32_e32 v238, 16, v166
	v_and_b32_e32 v239, s59, v166
	v_add_f32_e32 v230, v230, v238
	v_add_f32_e32 v230, v230, v239
	v_lshlrev_b32_e32 v238, 16, v167
	v_and_b32_e32 v239, s59, v167
	v_add_f32_e32 v230, v230, v238
	v_add_f32_e32 v230, v230, v239
	v_lshlrev_b32_e32 v238, 16, v168
	v_and_b32_e32 v239, s59, v168
	v_add_f32_e32 v231, v238, v239
	v_lshlrev_b32_e32 v238, 16, v169
	v_and_b32_e32 v239, s59, v169
	v_add_f32_e32 v231, v231, v238
	v_add_f32_e32 v231, v231, v239
	v_lshlrev_b32_e32 v238, 16, v170
	v_and_b32_e32 v239, s59, v170
	v_add_f32_e32 v231, v231, v238
	v_add_f32_e32 v231, v231, v239
	v_lshlrev_b32_e32 v238, 16, v171
	v_and_b32_e32 v239, s59, v171
	v_add_f32_e32 v231, v231, v238
	v_add_f32_e32 v231, v231, v239
	s_waitcnt lgkmcnt(0)
	v_add_f32_e32 v226, v226, v234
	v_add_f32_e32 v227, v227, v235
	v_add_f32_e32 v228, v228, v236
	v_add_f32_e32 v229, v229, v237
	ds_bpermute_b32 v234, v14, v226
	ds_bpermute_b32 v235, v14, v227
	ds_bpermute_b32 v236, v14, v228
	ds_bpermute_b32 v237, v14, v229
	v_lshlrev_b32_e32 v238, 16, v172
	v_and_b32_e32 v239, s59, v172
	v_add_f32_e32 v232, v238, v239
	v_lshlrev_b32_e32 v238, 16, v173
	v_and_b32_e32 v239, s59, v173
	v_add_f32_e32 v232, v232, v238
	v_add_f32_e32 v232, v232, v239
	v_lshlrev_b32_e32 v238, 16, v174
	v_and_b32_e32 v239, s59, v174
	v_add_f32_e32 v232, v232, v238
	v_add_f32_e32 v232, v232, v239
	v_lshlrev_b32_e32 v238, 16, v175
	v_and_b32_e32 v239, s59, v175
	v_add_f32_e32 v232, v232, v238
	v_add_f32_e32 v232, v232, v239
	v_lshlrev_b32_e32 v238, 16, v176
	v_and_b32_e32 v239, s59, v176
	v_add_f32_e32 v233, v238, v239
	v_lshlrev_b32_e32 v238, 16, v177
	v_and_b32_e32 v239, s59, v177
	v_add_f32_e32 v233, v233, v238
	v_add_f32_e32 v233, v233, v239
	v_lshlrev_b32_e32 v238, 16, v178
	v_and_b32_e32 v239, s59, v178
	v_add_f32_e32 v233, v233, v238
	v_add_f32_e32 v233, v233, v239
	v_lshlrev_b32_e32 v238, 16, v179
	v_and_b32_e32 v239, s59, v179
	v_add_f32_e32 v233, v233, v238
	v_add_f32_e32 v233, v233, v239
	s_nop 1
	v_add_f32_dpp v230, v230, v230 quad_perm:[1,0,3,2] row_mask:0xf bank_mask:0xf
	v_add_f32_dpp v231, v231, v231 quad_perm:[1,0,3,2] row_mask:0xf bank_mask:0xf
	v_add_f32_dpp v232, v232, v232 quad_perm:[1,0,3,2] row_mask:0xf bank_mask:0xf
	v_add_f32_dpp v233, v233, v233 quad_perm:[1,0,3,2] row_mask:0xf bank_mask:0xf
	v_add_f32_dpp v230, v230, v230 quad_perm:[2,3,0,1] row_mask:0xf bank_mask:0xf
	v_add_f32_dpp v231, v231, v231 quad_perm:[2,3,0,1] row_mask:0xf bank_mask:0xf
	v_add_f32_dpp v232, v232, v232 quad_perm:[2,3,0,1] row_mask:0xf bank_mask:0xf
	v_add_f32_dpp v233, v233, v233 quad_perm:[2,3,0,1] row_mask:0xf bank_mask:0xf
	v_add_f32_dpp v230, v230, v230 row_half_mirror row_mask:0xf bank_mask:0xf
	v_add_f32_dpp v231, v231, v231 row_half_mirror row_mask:0xf bank_mask:0xf
	v_add_f32_dpp v232, v232, v232 row_half_mirror row_mask:0xf bank_mask:0xf
	v_add_f32_dpp v233, v233, v233 row_half_mirror row_mask:0xf bank_mask:0xf
	s_waitcnt lgkmcnt(0)
	v_add_f32_e32 v226, v226, v234
	v_add_f32_e32 v227, v227, v235
	v_add_f32_e32 v228, v228, v236
	v_add_f32_e32 v229, v229, v237
	global_store_dwordx4 v17, v[164:167], s[36:37] sc1
	global_store_dwordx4 v18, v[168:171], s[36:37] sc1
	global_store_dwordx4 v19, v[172:175], s[36:37] sc1
	global_store_dwordx4 v20, v[176:179], s[36:37] sc1
	s_add_u32 s48, s38, s40
	s_addc_u32 s49, s39, 0
	s_mov_b64 exec, s[56:57]
	global_atomic_add_f32 v15, v230, s[38:39]
	global_atomic_add_f32 v15, v231, s[38:39] offset:32
	global_atomic_add_f32 v15, v232, s[38:39] offset:64
	global_atomic_add_f32 v15, v233, s[38:39] offset:96
	s_mov_b64 exec, s[64:65]
	global_atomic_add_f32 v16, v226, s[48:49]
	global_atomic_add_f32 v16, v227, s[48:49] offset:4
	global_atomic_add_f32 v16, v228, s[48:49] offset:8
	global_atomic_add_f32 v16, v229, s[48:49] offset:12
	s_mov_b64 exec, -1
	s_cmp_lt_u32 s30, 0x4000
	s_cbranch_scc1 .Lgv5_w1
	s_cmp_lt_u32 s30, 0x5000
	s_cbranch_scc1 .Lgv5_pg
	s_cmp_lt_u32 s30, 0x5800
	s_cbranch_scc1 .Lgv5_wq
	s_cmp_lt_u32 s30, 0x5a00
	s_cbranch_scc1 .Lgv5_wk
	s_cmp_lt_u32 s30, 0x5c00
	s_cbranch_scc1 .Lgv5_wv
	s_mov_b32 s12, 0
	s_load_dwordx2 s[4:5], s[18:19], 0x98
	s_load_dwordx2 s[6:7], s[18:19], 0x100
	s_load_dwordx2 s[8:9], s[18:19], 0x108
	s_mov_b32 s10, 11
	s_mov_b32 s11, 4
	s_mov_b32 s69, 0x2d200000
	s_mov_b32 s70, 0x2e200000
	s_mov_b32 s40, 0x3000
	s_mov_b32 s71, 0
	s_mov_b32 s72, 0
	s_branch .Lgv5_common

.Lgv5_common:
	s_lshr_b32 s13, s12, s11
	s_lshl_b32 s15, s13, s11
	s_sub_i32 s14, s12, s15
	s_add_i32 s15, s10, 6
	s_lshl_b32 s15, s13, s15
	s_lshl_b32 s21, s14, 7
	s_add_i32 s15, s15, s21
	s_lshl_b32 s29, 8, s10
	v_lshlrev_b32_e32 v4, s10, v2
	v_lshl_add_u32 v4, v3, 4, v4
	s_lshl_b32 s21, s13, 8
	s_waitcnt lgkmcnt(0)
	s_add_u32 s4, s4, s71
	s_addc_u32 s5, s5, 0
	s_add_u32 s4, s4, s15
	s_addc_u32 s5, s5, 0
	s_add_u32 s6, s6, s72
	s_addc_u32 s7, s7, 0
	s_add_u32 s6, s6, s21
	s_addc_u32 s7, s7, 0
	s_add_u32 s8, s8, s72
	s_addc_u32 s9, s9, 0
	s_add_u32 s8, s8, s21
	s_addc_u32 s9, s9, 0
	global_load_dwordx4 v[100:103], v4, s[4:5] nt
	s_add_u32 s4, s4, s29
	s_addc_u32 s5, s5, 0
	global_load_dwordx4 v[104:107], v4, s[4:5] nt
	s_add_u32 s4, s4, s29
	s_addc_u32 s5, s5, 0
	global_load_dwordx4 v[108:111], v4, s[4:5] nt
	s_add_u32 s4, s4, s29
	s_addc_u32 s5, s5, 0
	global_load_dwordx4 v[112:115], v4, s[4:5] nt
	s_add_u32 s4, s4, s29
	s_addc_u32 s5, s5, 0
	global_load_dwordx4 v[116:119], v4, s[4:5] nt
	s_add_u32 s4, s4, s29
	s_addc_u32 s5, s5, 0
	global_load_dwordx4 v[120:123], v4, s[4:5] nt
	s_add_u32 s4, s4, s29
	s_addc_u32 s5, s5, 0
	global_load_dwordx4 v[124:127], v4, s[4:5] nt
	s_add_u32 s4, s4, s29
	s_addc_u32 s5, s5, 0
	global_load_dwordx4 v[128:131], v4, s[4:5] nt
	global_load_dword v206, v5, s[6:7]
	global_load_dword v207, v5, s[8:9]
	s_lshl_b32 s15, s14, 17
	s_lshl_b32 s21, s13, 7
	s_add_i32 s15, s15, s21
	s_add_u32 s36, s16, s69
	s_addc_u32 s37, s17, 0
	s_add_u32 s36, s36, s15
	s_addc_u32 s37, s37, 0
	s_lshl_b32 s15, s14, 7
	s_add_u32 s38, s16, s70
	s_addc_u32 s39, s17, 0
	s_add_u32 s38, s38, s15
	s_addc_u32 s39, s39, 0
	s_addk_i32 s30, 0x800
	s_add_i32 s3, s3, -1
	s_cmp_lg_u32 s3, 0
	s_cbranch_scc1 .Lgv_loop
	s_waitcnt vmcnt(22)
	ds_write_b32 v10, v208
	ds_write_b32 v10, v209 offset:256
	ds_read_b128 v[210:213], v11
	ds_read_b128 v[214:217], v11 offset:16
	ds_read_b128 v[218:221], v11 offset:256
	ds_read_b128 v[222:225], v11 offset:272
	s_waitcnt lgkmcnt(0)
	v_mul_f32_e32 v226, v132, v218
	v_mul_f32_e32 v132, v132, v210
	v_mul_f32_e32 v227, v133, v218
	v_mul_f32_e32 v133, v133, v210
	v_mul_f32_e32 v228, v134, v218
	v_mul_f32_e32 v134, v134, v210
	v_mul_f32_e32 v229, v135, v218
	v_mul_f32_e32 v135, v135, v210
	v_fmac_f32_e32 v226, v136, v219
	v_mul_f32_e32 v136, v136, v211
	v_fmac_f32_e32 v227, v137, v219
	v_mul_f32_e32 v137, v137, v211
	v_fmac_f32_e32 v228, v138, v219
	v_mul_f32_e32 v138, v138, v211
	v_fmac_f32_e32 v229, v139, v219
	v_mul_f32_e32 v139, v139, v211
	v_fmac_f32_e32 v226, v140, v220
	v_mul_f32_e32 v140, v140, v212
	v_fmac_f32_e32 v227, v141, v220
	v_mul_f32_e32 v141, v141, v212
	v_fmac_f32_e32 v228, v142, v220
	v_mul_f32_e32 v142, v142, v212
	v_fmac_f32_e32 v229, v143, v220
	v_mul_f32_e32 v143, v143, v212
	v_fmac_f32_e32 v226, v144, v221
	v_mul_f32_e32 v144, v144, v213
	v_fmac_f32_e32 v227, v145, v221
	v_mul_f32_e32 v145, v145, v213
	v_fmac_f32_e32 v228, v146, v221
	v_mul_f32_e32 v146, v146, v213
	v_fmac_f32_e32 v229, v147, v221
	v_mul_f32_e32 v147, v147, v213
	v_fmac_f32_e32 v226, v148, v222
	v_mul_f32_e32 v148, v148, v214
	v_fmac_f32_e32 v227, v149, v222
	v_mul_f32_e32 v149, v149, v214
	v_fmac_f32_e32 v228, v150, v222
	v_mul_f32_e32 v150, v150, v214
	v_fmac_f32_e32 v229, v151, v222
	v_mul_f32_e32 v151, v151, v214
	v_fmac_f32_e32 v226, v152, v223
	v_mul_f32_e32 v152, v152, v215
	v_fmac_f32_e32 v227, v153, v223
	v_mul_f32_e32 v153, v153, v215
	v_fmac_f32_e32 v228, v154, v223
	v_mul_f32_e32 v154, v154, v215
	v_fmac_f32_e32 v229, v155, v223
	v_mul_f32_e32 v155, v155, v215
	v_fmac_f32_e32 v226, v156, v224
	v_mul_f32_e32 v156, v156, v216
	v_fmac_f32_e32 v227, v157, v224
	v_mul_f32_e32 v157, v157, v216
	v_fmac_f32_e32 v228, v158, v224
	v_mul_f32_e32 v158, v158, v216
	v_fmac_f32_e32 v229, v159, v224
	v_mul_f32_e32 v159, v159, v216
	v_fmac_f32_e32 v226, v160, v225
	v_mul_f32_e32 v160, v160, v217
	v_fmac_f32_e32 v227, v161, v225
	v_mul_f32_e32 v161, v161, v217
	v_fmac_f32_e32 v228, v162, v225
	v_mul_f32_e32 v162, v162, v217
	v_fmac_f32_e32 v229, v163, v225
	v_mul_f32_e32 v163, v163, v217
	ds_write_b128 v21, v[132:135]
	ds_write_b128 v22, v[136:139] offset:1024
	ds_write_b128 v23, v[140:143] offset:2048
	ds_write_b128 v24, v[144:147] offset:3072
	ds_write_b128 v25, v[148:151] offset:4096
	ds_write_b128 v26, v[152:155] offset:5120
	ds_write_b128 v27, v[156:159] offset:6144
	ds_write_b128 v28, v[160:163] offset:7168
	ds_read2_b32 v[132:133], v29 offset1:32
	ds_read2_b32 v[134:135], v29 offset0:64 offset1:96
	ds_read2_b32 v[136:137], v29 offset0:128 offset1:160
	ds_read2_b32 v[138:139], v29 offset0:192 offset1:224
	ds_read2_b32 v[140:141], v30 offset1:32
	ds_read2_b32 v[142:143], v30 offset0:64 offset1:96
	ds_read2_b32 v[144:145], v30 offset0:128 offset1:160
	ds_read2_b32 v[146:147], v30 offset0:192 offset1:224
	ds_read2_b32 v[148:149], v31 offset1:32
	ds_read2_b32 v[150:151], v31 offset0:64 offset1:96
	ds_read2_b32 v[152:153], v31 offset0:128 offset1:160
	ds_read2_b32 v[154:155], v31 offset0:192 offset1:224
	ds_read2_b32 v[156:157], v32 offset1:32
	ds_read2_b32 v[158:159], v32 offset0:64 offset1:96
	ds_read2_b32 v[160:161], v32 offset0:128 offset1:160
	ds_read2_b32 v[162:163], v32 offset0:192 offset1:224
	ds_bpermute_b32 v234, v12, v226
	ds_bpermute_b32 v235, v12, v227
	ds_bpermute_b32 v236, v12, v228
	ds_bpermute_b32 v237, v12, v229
	s_waitcnt lgkmcnt(4)
	v_cvt_pk_bf16_f32 v190, v132, v133
	v_cvt_pk_bf16_f32 v191, v134, v135
	v_cvt_pk_bf16_f32 v192, v136, v137
	v_cvt_pk_bf16_f32 v193, v138, v139
	v_cvt_pk_bf16_f32 v194, v140, v141
	v_cvt_pk_bf16_f32 v195, v142, v143
	v_cvt_pk_bf16_f32 v196, v144, v145
	v_cvt_pk_bf16_f32 v197, v146, v147
	v_cvt_pk_bf16_f32 v198, v148, v149
	v_cvt_pk_bf16_f32 v199, v150, v151
	v_cvt_pk_bf16_f32 v200, v152, v153
	v_cvt_pk_bf16_f32 v201, v154, v155
	v_cvt_pk_bf16_f32 v202, v156, v157
	v_cvt_pk_bf16_f32 v203, v158, v159
	v_cvt_pk_bf16_f32 v204, v160, v161
	v_cvt_pk_bf16_f32 v205, v162, v163
	s_waitcnt lgkmcnt(0)
	v_add_f32_e32 v226, v226, v234
	v_add_f32_e32 v227, v227, v235
	v_add_f32_e32 v228, v228, v236
	v_add_f32_e32 v229, v229, v237
	ds_bpermute_b32 v234, v13, v226
	ds_bpermute_b32 v235, v13, v227
	ds_bpermute_b32 v236, v13, v228
	ds_bpermute_b32 v237, v13, v229
	v_lshlrev_b32_e32 v238, 16, v190
	v_and_b32_e32 v239, s59, v190
	v_add_f32_e32 v230, v238, v239
	v_lshlrev_b32_e32 v238, 16, v191
	v_and_b32_e32 v239, s59, v191
	v_add_f32_e32 v230, v230, v238
	v_add_f32_e32 v230, v230, v239
	v_lshlrev_b32_e32 v238, 16, v192
	v_and_b32_e32 v239, s59, v192
	v_add_f32_e32 v230, v230, v238
	v_add_f32_e32 v230, v230, v239
	v_lshlrev_b32_e32 v238, 16, v193
	v_and_b32_e32 v239, s59, v193
	v_add_f32_e32 v230, v230, v238
	v_add_f32_e32 v230, v230, v239
	v_lshlrev_b32_e32 v238, 16, v194
	v_and_b32_e32 v239, s59, v194
	v_add_f32_e32 v231, v238, v239
	v_lshlrev_b32_e32 v238, 16, v195
	v_and_b32_e32 v239, s59, v195
	v_add_f32_e32 v231, v231, v238
	v_add_f32_e32 v231, v231, v239
	v_lshlrev_b32_e32 v238, 16, v196
	v_and_b32_e32 v239, s59, v196
	v_add_f32_e32 v231, v231, v238
	v_add_f32_e32 v231, v231, v239
	v_lshlrev_b32_e32 v238, 16, v197
	v_and_b32_e32 v239, s59, v197
	v_add_f32_e32 v231, v231, v238
	v_add_f32_e32 v231, v231, v239
	s_waitcnt lgkmcnt(0)
	v_add_f32_e32 v226, v226, v234
	v_add_f32_e32 v227, v227, v235
	v_add_f32_e32 v228, v228, v236
	v_add_f32_e32 v229, v229, v237
	ds_bpermute_b32 v234, v14, v226
	ds_bpermute_b32 v235, v14, v227
	ds_bpermute_b32 v236, v14, v228
	ds_bpermute_b32 v237, v14, v229
	v_lshlrev_b32_e32 v238, 16, v198
	v_and_b32_e32 v239, s59, v198
	v_add_f32_e32 v232, v238, v239
	v_lshlrev_b32_e32 v238, 16, v199
	v_and_b32_e32 v239, s59, v199
	v_add_f32_e32 v232, v232, v238
	v_add_f32_e32 v232, v232, v239
	v_lshlrev_b32_e32 v238, 16, v200
	v_and_b32_e32 v239, s59, v200
	v_add_f32_e32 v232, v232, v238
	v_add_f32_e32 v232, v232, v239
	v_lshlrev_b32_e32 v238, 16, v201
	v_and_b32_e32 v239, s59, v201
	v_add_f32_e32 v232, v232, v238
	v_add_f32_e32 v232, v232, v239
	v_lshlrev_b32_e32 v238, 16, v202
	v_and_b32_e32 v239, s59, v202
	v_add_f32_e32 v233, v238, v239
	v_lshlrev_b32_e32 v238, 16, v203
	v_and_b32_e32 v239, s59, v203
	v_add_f32_e32 v233, v233, v238
	v_add_f32_e32 v233, v233, v239
	v_lshlrev_b32_e32 v238, 16, v204
	v_and_b32_e32 v239, s59, v204
	v_add_f32_e32 v233, v233, v238
	v_add_f32_e32 v233, v233, v239
	v_lshlrev_b32_e32 v238, 16, v205
	v_and_b32_e32 v239, s59, v205
	v_add_f32_e32 v233, v233, v238
	v_add_f32_e32 v233, v233, v239
	s_nop 1
	v_add_f32_dpp v230, v230, v230 quad_perm:[1,0,3,2] row_mask:0xf bank_mask:0xf
	v_add_f32_dpp v231, v231, v231 quad_perm:[1,0,3,2] row_mask:0xf bank_mask:0xf
	v_add_f32_dpp v232, v232, v232 quad_perm:[1,0,3,2] row_mask:0xf bank_mask:0xf
	v_add_f32_dpp v233, v233, v233 quad_perm:[1,0,3,2] row_mask:0xf bank_mask:0xf
	v_add_f32_dpp v230, v230, v230 quad_perm:[2,3,0,1] row_mask:0xf bank_mask:0xf
	v_add_f32_dpp v231, v231, v231 quad_perm:[2,3,0,1] row_mask:0xf bank_mask:0xf
	v_add_f32_dpp v232, v232, v232 quad_perm:[2,3,0,1] row_mask:0xf bank_mask:0xf
	v_add_f32_dpp v233, v233, v233 quad_perm:[2,3,0,1] row_mask:0xf bank_mask:0xf
	v_add_f32_dpp v230, v230, v230 row_half_mirror row_mask:0xf bank_mask:0xf
	v_add_f32_dpp v231, v231, v231 row_half_mirror row_mask:0xf bank_mask:0xf
	v_add_f32_dpp v232, v232, v232 row_half_mirror row_mask:0xf bank_mask:0xf
	v_add_f32_dpp v233, v233, v233 row_half_mirror row_mask:0xf bank_mask:0xf
	s_waitcnt lgkmcnt(0)
	v_add_f32_e32 v226, v226, v234
	v_add_f32_e32 v227, v227, v235
	v_add_f32_e32 v228, v228, v236
	v_add_f32_e32 v229, v229, v237
	global_store_dwordx4 v17, v[190:193], s[42:43] sc1
	global_store_dwordx4 v18, v[194:197], s[42:43] sc1
	global_store_dwordx4 v19, v[198:201], s[42:43] sc1
	global_store_dwordx4 v20, v[202:205], s[42:43] sc1
	s_add_u32 s48, s44, s47
	s_addc_u32 s49, s45, 0
	s_mov_b64 exec, s[56:57]
	global_atomic_add_f32 v15, v230, s[44:45]
	global_atomic_add_f32 v15, v231, s[44:45] offset:32
	global_atomic_add_f32 v15, v232, s[44:45] offset:64
	global_atomic_add_f32 v15, v233, s[44:45] offset:96
	s_mov_b64 exec, s[64:65]
	global_atomic_add_f32 v16, v226, s[48:49]
	global_atomic_add_f32 v16, v227, s[48:49] offset:4
	global_atomic_add_f32 v16, v228, s[48:49] offset:8
	global_atomic_add_f32 v16, v229, s[48:49] offset:12
	s_mov_b64 exec, -1
	s_waitcnt vmcnt(0) lgkmcnt(0)
.Lgv_end:
.Lw2l_begin:
	s_cmp_eq_u32 s99, 1
	s_cbranch_scc1 .Lw2l_end
	v_readlane_b32 s43, v255, 8
	v_lshrrev_b32_e32 v2, 3, v244
	v_and_b32_e32 v3, 7, v244
	v_lshlrev_b32_e32 v4, 13, v2
	v_lshl_add_u32 v4, v3, 4, v4
	s_lshl_b32 s31, s85, 14
	v_lshlrev_b32_e32 v5, 7, v2
	v_add_u32_e32 v5, s31, v5
	v_xor_b32_e32 v6, 0, v3
	v_lshl_add_u32 v110, v6, 4, v5
	v_xor_b32_e32 v6, 1, v3
	v_lshl_add_u32 v111, v6, 4, v5
	v_xor_b32_e32 v6, 2, v3
	v_lshl_add_u32 v112, v6, 4, v5
	v_xor_b32_e32 v6, 3, v3
	v_lshl_add_u32 v113, v6, 4, v5
	v_xor_b32_e32 v6, 4, v3
	v_lshl_add_u32 v114, v6, 4, v5
	v_xor_b32_e32 v6, 5, v3
	v_lshl_add_u32 v115, v6, 4, v5
	v_xor_b32_e32 v6, 6, v3
	v_lshl_add_u32 v116, v6, 4, v5
	v_xor_b32_e32 v6, 7, v3
	v_lshl_add_u32 v117, v6, 4, v5
	v_lshlrev_b32_e32 v7, 10, v3
	v_add_u32_e32 v7, s31, v7
	v_add_u32_e32 v8, 0, v2
	v_lshrrev_b32_e32 v9, 2, v8
	v_xor_b32_e32 v9, v9, v3
	v_and_b32_e32 v8, 3, v8
	v_lshl_add_u32 v8, v9, 2, v8
	v_lshl_add_u32 v118, v8, 2, v7
	v_add_u32_e32 v8, 8, v2
	v_lshrrev_b32_e32 v9, 2, v8
	v_xor_b32_e32 v9, v9, v3
	v_and_b32_e32 v8, 3, v8
	v_lshl_add_u32 v8, v9, 2, v8
	v_lshl_add_u32 v119, v8, 2, v7
	v_add_u32_e32 v8, 16, v2
	v_lshrrev_b32_e32 v9, 2, v8
	v_xor_b32_e32 v9, v9, v3
	v_and_b32_e32 v8, 3, v8
	v_lshl_add_u32 v8, v9, 2, v8
	v_lshl_add_u32 v120, v8, 2, v7
	v_add_u32_e32 v8, 24, v2
	v_lshrrev_b32_e32 v9, 2, v8
	v_xor_b32_e32 v9, v9, v3
	v_and_b32_e32 v8, 3, v8
	v_lshl_add_u32 v8, v9, 2, v8
	v_lshl_add_u32 v121, v8, 2, v7
	s_load_dwordx2 s[26:27], s[86:87], 0xd8
	s_load_dwordx2 s[28:29], s[86:87], 0x118
	s_mov_b32 s30, s43
	v_lshlrev_b32_e32 v74, 14, v2
	v_lshl_add_u32 v74, v3, 4, v74
	v_add_u32_e32 v75, 0x20000, v74
	v_add_u32_e32 v76, 0x40000, v74
	v_add_u32_e32 v77, 0x60000, v74
	s_waitcnt lgkmcnt(0)
	s_add_u32 s28, s28, 0x3200000
	s_addc_u32 s29, s29, 0
	s_lshr_b32 s46, s30, 6
	s_and_b32 s47, s30, 63
	s_mov_b32 s40, s30
	s_lshl_b32 s36, s46, 19
	s_lshl_b32 s37, s47, 7
	s_add_i32 s36, s36, s37
	s_add_u32 s38, s26, s36
	s_addc_u32 s39, s27, 0
	global_load_dwordx4 v[10:13], v4, s[38:39] nt
	s_add_u32 s38, s38, 0x10000
	s_addc_u32 s39, s39, 0
	global_load_dwordx4 v[14:17], v4, s[38:39] nt
	s_add_u32 s38, s38, 0x10000
	s_addc_u32 s39, s39, 0
	global_load_dwordx4 v[18:21], v4, s[38:39] nt
	s_add_u32 s38, s38, 0x10000
	s_addc_u32 s39, s39, 0
	global_load_dwordx4 v[22:25], v4, s[38:39] nt
	s_add_u32 s38, s38, 0x10000
	s_addc_u32 s39, s39, 0
	global_load_dwordx4 v[26:29], v4, s[38:39] nt
	s_add_u32 s38, s38, 0x10000
	s_addc_u32 s39, s39, 0
	global_load_dwordx4 v[30:33], v4, s[38:39] nt
	s_add_u32 s38, s38, 0x10000
	s_addc_u32 s39, s39, 0
	global_load_dwordx4 v[34:37], v4, s[38:39] nt
	s_add_u32 s38, s38, 0x10000
	s_addc_u32 s39, s39, 0
	global_load_dwordx4 v[38:41], v4, s[38:39] nt
	s_addk_i32 s30, 0x800
	s_and_b32 s30, s30, 0x1fff
	s_lshr_b32 s46, s30, 6
	s_and_b32 s47, s30, 63
	s_mov_b32 s41, s30
	s_lshl_b32 s36, s46, 19
	s_lshl_b32 s37, s47, 7
	s_add_i32 s36, s36, s37
	s_add_u32 s38, s26, s36
	s_addc_u32 s39, s27, 0
	global_load_dwordx4 v[42:45], v4, s[38:39] nt
	s_add_u32 s38, s38, 0x10000
	s_addc_u32 s39, s39, 0
	global_load_dwordx4 v[46:49], v4, s[38:39] nt
	s_add_u32 s38, s38, 0x10000
	s_addc_u32 s39, s39, 0
	global_load_dwordx4 v[50:53], v4, s[38:39] nt
	s_add_u32 s38, s38, 0x10000
	s_addc_u32 s39, s39, 0
	global_load_dwordx4 v[54:57], v4, s[38:39] nt
	s_add_u32 s38, s38, 0x10000
	s_addc_u32 s39, s39, 0
	global_load_dwordx4 v[58:61], v4, s[38:39] nt
	s_add_u32 s38, s38, 0x10000
	s_addc_u32 s39, s39, 0
	global_load_dwordx4 v[62:65], v4, s[38:39] nt
	s_add_u32 s38, s38, 0x10000
	s_addc_u32 s39, s39, 0
	global_load_dwordx4 v[66:69], v4, s[38:39] nt
	s_add_u32 s38, s38, 0x10000
	s_addc_u32 s39, s39, 0
	global_load_dwordx4 v[70:73], v4, s[38:39] nt
	s_addk_i32 s30, 0x800
	s_and_b32 s30, s30, 0x1fff
	s_waitcnt vmcnt(8)
	ds_write_b128 v110, v[10:13]
	ds_write_b128 v111, v[14:17] offset:1024
	ds_write_b128 v112, v[18:21] offset:2048
	ds_write_b128 v113, v[22:25] offset:3072
	ds_write_b128 v114, v[26:29] offset:4096
	ds_write_b128 v115, v[30:33] offset:5120
	ds_write_b128 v116, v[34:37] offset:6144
	ds_write_b128 v117, v[38:41] offset:7168
	ds_read2_b32 v[10:11], v118 offset1:32
	ds_read2_b32 v[12:13], v118 offset0:64 offset1:96
	ds_read2_b32 v[14:15], v118 offset0:128 offset1:160
	ds_read2_b32 v[16:17], v118 offset0:192 offset1:224
	ds_read2_b32 v[18:19], v119 offset1:32
	ds_read2_b32 v[20:21], v119 offset0:64 offset1:96
	ds_read2_b32 v[22:23], v119 offset0:128 offset1:160
	ds_read2_b32 v[24:25], v119 offset0:192 offset1:224
	ds_read2_b32 v[26:27], v120 offset1:32
	ds_read2_b32 v[28:29], v120 offset0:64 offset1:96
	ds_read2_b32 v[30:31], v120 offset0:128 offset1:160
	ds_read2_b32 v[32:33], v120 offset0:192 offset1:224
	ds_read2_b32 v[34:35], v121 offset1:32
	ds_read2_b32 v[36:37], v121 offset0:64 offset1:96
	ds_read2_b32 v[38:39], v121 offset0:128 offset1:160
	ds_read2_b32 v[40:41], v121 offset0:192 offset1:224
	s_lshr_b32 s46, s40, 6
	s_and_b32 s47, s40, 63
	s_lshl_b32 s36, s47, 19
	s_lshl_b32 s37, s46, 7
	s_add_i32 s36, s36, s37
	s_add_u32 s38, s28, s36
	s_addc_u32 s39, s29, 0
	s_waitcnt lgkmcnt(12)
	v_cvt_pk_bf16_f32 v78, v10, v11
	v_cvt_pk_bf16_f32 v79, v12, v13
	v_cvt_pk_bf16_f32 v80, v14, v15
	v_cvt_pk_bf16_f32 v81, v16, v17
	s_waitcnt lgkmcnt(8)
	v_cvt_pk_bf16_f32 v82, v18, v19
	v_cvt_pk_bf16_f32 v83, v20, v21
	v_cvt_pk_bf16_f32 v84, v22, v23
	v_cvt_pk_bf16_f32 v85, v24, v25
	s_waitcnt lgkmcnt(4)
	v_cvt_pk_bf16_f32 v86, v26, v27
	v_cvt_pk_bf16_f32 v87, v28, v29
	v_cvt_pk_bf16_f32 v88, v30, v31
	v_cvt_pk_bf16_f32 v89, v32, v33
	s_waitcnt lgkmcnt(0)
	v_cvt_pk_bf16_f32 v90, v34, v35
	v_cvt_pk_bf16_f32 v91, v36, v37
	v_cvt_pk_bf16_f32 v92, v38, v39
	v_cvt_pk_bf16_f32 v93, v40, v41
	global_store_dwordx4 v74, v[78:81], s[38:39] sc1
	global_store_dwordx4 v75, v[82:85], s[38:39] sc1
	global_store_dwordx4 v76, v[86:89], s[38:39] sc1
	global_store_dwordx4 v77, v[90:93], s[38:39] sc1
	s_lshr_b32 s46, s30, 6
	s_and_b32 s47, s30, 63
	s_mov_b32 s40, s30
	s_lshl_b32 s36, s46, 19
	s_lshl_b32 s37, s47, 7
	s_add_i32 s36, s36, s37
	s_add_u32 s38, s26, s36
	s_addc_u32 s39, s27, 0
	global_load_dwordx4 v[10:13], v4, s[38:39] nt
	s_add_u32 s38, s38, 0x10000
	s_addc_u32 s39, s39, 0
	global_load_dwordx4 v[14:17], v4, s[38:39] nt
	s_add_u32 s38, s38, 0x10000
	s_addc_u32 s39, s39, 0
	global_load_dwordx4 v[18:21], v4, s[38:39] nt
	s_add_u32 s38, s38, 0x10000
	s_addc_u32 s39, s39, 0
	global_load_dwordx4 v[22:25], v4, s[38:39] nt
	s_add_u32 s38, s38, 0x10000
	s_addc_u32 s39, s39, 0
	global_load_dwordx4 v[26:29], v4, s[38:39] nt
	s_add_u32 s38, s38, 0x10000
	s_addc_u32 s39, s39, 0
	global_load_dwordx4 v[30:33], v4, s[38:39] nt
	s_add_u32 s38, s38, 0x10000
	s_addc_u32 s39, s39, 0
	global_load_dwordx4 v[34:37], v4, s[38:39] nt
	s_add_u32 s38, s38, 0x10000
	s_addc_u32 s39, s39, 0
	global_load_dwordx4 v[38:41], v4, s[38:39] nt
	s_addk_i32 s30, 0x800
	s_and_b32 s30, s30, 0x1fff
	s_waitcnt vmcnt(12)
	ds_write_b128 v110, v[42:45]
	ds_write_b128 v111, v[46:49] offset:1024
	ds_write_b128 v112, v[50:53] offset:2048
	ds_write_b128 v113, v[54:57] offset:3072
	ds_write_b128 v114, v[58:61] offset:4096
	ds_write_b128 v115, v[62:65] offset:5120
	ds_write_b128 v116, v[66:69] offset:6144
	ds_write_b128 v117, v[70:73] offset:7168
	ds_read2_b32 v[42:43], v118 offset1:32
	ds_read2_b32 v[44:45], v118 offset0:64 offset1:96
	ds_read2_b32 v[46:47], v118 offset0:128 offset1:160
	ds_read2_b32 v[48:49], v118 offset0:192 offset1:224
	ds_read2_b32 v[50:51], v119 offset1:32
	ds_read2_b32 v[52:53], v119 offset0:64 offset1:96
	ds_read2_b32 v[54:55], v119 offset0:128 offset1:160
	ds_read2_b32 v[56:57], v119 offset0:192 offset1:224
	ds_read2_b32 v[58:59], v120 offset1:32
	ds_read2_b32 v[60:61], v120 offset0:64 offset1:96
	ds_read2_b32 v[62:63], v120 offset0:128 offset1:160
	ds_read2_b32 v[64:65], v120 offset0:192 offset1:224
	ds_read2_b32 v[66:67], v121 offset1:32
	ds_read2_b32 v[68:69], v121 offset0:64 offset1:96
	ds_read2_b32 v[70:71], v121 offset0:128 offset1:160
	ds_read2_b32 v[72:73], v121 offset0:192 offset1:224
	s_lshr_b32 s46, s41, 6
	s_and_b32 s47, s41, 63
	s_lshl_b32 s36, s47, 19
	s_lshl_b32 s37, s46, 7
	s_add_i32 s36, s36, s37
	s_add_u32 s38, s28, s36
	s_addc_u32 s39, s29, 0
	s_waitcnt lgkmcnt(12)
	v_cvt_pk_bf16_f32 v94, v42, v43
	v_cvt_pk_bf16_f32 v95, v44, v45
	v_cvt_pk_bf16_f32 v96, v46, v47
	v_cvt_pk_bf16_f32 v97, v48, v49
	s_waitcnt lgkmcnt(8)
	v_cvt_pk_bf16_f32 v98, v50, v51
	v_cvt_pk_bf16_f32 v99, v52, v53
	v_cvt_pk_bf16_f32 v100, v54, v55
	v_cvt_pk_bf16_f32 v101, v56, v57
	s_waitcnt lgkmcnt(4)
	v_cvt_pk_bf16_f32 v102, v58, v59
	v_cvt_pk_bf16_f32 v103, v60, v61
	v_cvt_pk_bf16_f32 v104, v62, v63
	v_cvt_pk_bf16_f32 v105, v64, v65
	s_waitcnt lgkmcnt(0)
	v_cvt_pk_bf16_f32 v106, v66, v67
	v_cvt_pk_bf16_f32 v107, v68, v69
	v_cvt_pk_bf16_f32 v108, v70, v71
	v_cvt_pk_bf16_f32 v109, v72, v73
	global_store_dwordx4 v74, v[94:97], s[38:39] sc1
	global_store_dwordx4 v75, v[98:101], s[38:39] sc1
	global_store_dwordx4 v76, v[102:105], s[38:39] sc1
	global_store_dwordx4 v77, v[106:109], s[38:39] sc1
	s_lshr_b32 s46, s30, 6
	s_and_b32 s47, s30, 63
	s_mov_b32 s41, s30
	s_lshl_b32 s36, s46, 19
	s_lshl_b32 s37, s47, 7
	s_add_i32 s36, s36, s37
	s_add_u32 s38, s26, s36
	s_addc_u32 s39, s27, 0
	global_load_dwordx4 v[42:45], v4, s[38:39] nt
	s_add_u32 s38, s38, 0x10000
	s_addc_u32 s39, s39, 0
	global_load_dwordx4 v[46:49], v4, s[38:39] nt
	s_add_u32 s38, s38, 0x10000
	s_addc_u32 s39, s39, 0
	global_load_dwordx4 v[50:53], v4, s[38:39] nt
	s_add_u32 s38, s38, 0x10000
	s_addc_u32 s39, s39, 0
	global_load_dwordx4 v[54:57], v4, s[38:39] nt
	s_add_u32 s38, s38, 0x10000
	s_addc_u32 s39, s39, 0
	global_load_dwordx4 v[58:61], v4, s[38:39] nt
	s_add_u32 s38, s38, 0x10000
	s_addc_u32 s39, s39, 0
	global_load_dwordx4 v[62:65], v4, s[38:39] nt
	s_add_u32 s38, s38, 0x10000
	s_addc_u32 s39, s39, 0
	global_load_dwordx4 v[66:69], v4, s[38:39] nt
	s_add_u32 s38, s38, 0x10000
	s_addc_u32 s39, s39, 0
	global_load_dwordx4 v[70:73], v4, s[38:39] nt
	s_addk_i32 s30, 0x800
	s_and_b32 s30, s30, 0x1fff
	s_waitcnt vmcnt(12)
	ds_write_b128 v110, v[10:13]
	ds_write_b128 v111, v[14:17] offset:1024
	ds_write_b128 v112, v[18:21] offset:2048
	ds_write_b128 v113, v[22:25] offset:3072
	ds_write_b128 v114, v[26:29] offset:4096
	ds_write_b128 v115, v[30:33] offset:5120
	ds_write_b128 v116, v[34:37] offset:6144
	ds_write_b128 v117, v[38:41] offset:7168
	ds_read2_b32 v[10:11], v118 offset1:32
	ds_read2_b32 v[12:13], v118 offset0:64 offset1:96
	ds_read2_b32 v[14:15], v118 offset0:128 offset1:160
	ds_read2_b32 v[16:17], v118 offset0:192 offset1:224
	ds_read2_b32 v[18:19], v119 offset1:32
	ds_read2_b32 v[20:21], v119 offset0:64 offset1:96
	ds_read2_b32 v[22:23], v119 offset0:128 offset1:160
	ds_read2_b32 v[24:25], v119 offset0:192 offset1:224
	ds_read2_b32 v[26:27], v120 offset1:32
	ds_read2_b32 v[28:29], v120 offset0:64 offset1:96
	ds_read2_b32 v[30:31], v120 offset0:128 offset1:160
	ds_read2_b32 v[32:33], v120 offset0:192 offset1:224
	ds_read2_b32 v[34:35], v121 offset1:32
	ds_read2_b32 v[36:37], v121 offset0:64 offset1:96
	ds_read2_b32 v[38:39], v121 offset0:128 offset1:160
	ds_read2_b32 v[40:41], v121 offset0:192 offset1:224
	s_lshr_b32 s46, s40, 6
	s_and_b32 s47, s40, 63
	s_lshl_b32 s36, s47, 19
	s_lshl_b32 s37, s46, 7
	s_add_i32 s36, s36, s37
	s_add_u32 s38, s28, s36
	s_addc_u32 s39, s29, 0
	s_waitcnt lgkmcnt(12)
	v_cvt_pk_bf16_f32 v78, v10, v11
	v_cvt_pk_bf16_f32 v79, v12, v13
	v_cvt_pk_bf16_f32 v80, v14, v15
	v_cvt_pk_bf16_f32 v81, v16, v17
	s_waitcnt lgkmcnt(8)
	v_cvt_pk_bf16_f32 v82, v18, v19
	v_cvt_pk_bf16_f32 v83, v20, v21
	v_cvt_pk_bf16_f32 v84, v22, v23
	v_cvt_pk_bf16_f32 v85, v24, v25
	s_waitcnt lgkmcnt(4)
	v_cvt_pk_bf16_f32 v86, v26, v27
	v_cvt_pk_bf16_f32 v87, v28, v29
	v_cvt_pk_bf16_f32 v88, v30, v31
	v_cvt_pk_bf16_f32 v89, v32, v33
	s_waitcnt lgkmcnt(0)
	v_cvt_pk_bf16_f32 v90, v34, v35
	v_cvt_pk_bf16_f32 v91, v36, v37
	v_cvt_pk_bf16_f32 v92, v38, v39
	v_cvt_pk_bf16_f32 v93, v40, v41
	global_store_dwordx4 v74, v[78:81], s[38:39] sc1
	global_store_dwordx4 v75, v[82:85], s[38:39] sc1
	global_store_dwordx4 v76, v[86:89], s[38:39] sc1
	global_store_dwordx4 v77, v[90:93], s[38:39] sc1
	s_waitcnt vmcnt(4)
	ds_write_b128 v110, v[42:45]
	ds_write_b128 v111, v[46:49] offset:1024
	ds_write_b128 v112, v[50:53] offset:2048
	ds_write_b128 v113, v[54:57] offset:3072
	ds_write_b128 v114, v[58:61] offset:4096
	ds_write_b128 v115, v[62:65] offset:5120
	ds_write_b128 v116, v[66:69] offset:6144
	ds_write_b128 v117, v[70:73] offset:7168
	ds_read2_b32 v[42:43], v118 offset1:32
	ds_read2_b32 v[44:45], v118 offset0:64 offset1:96
	ds_read2_b32 v[46:47], v118 offset0:128 offset1:160
	ds_read2_b32 v[48:49], v118 offset0:192 offset1:224
	ds_read2_b32 v[50:51], v119 offset1:32
	ds_read2_b32 v[52:53], v119 offset0:64 offset1:96
	ds_read2_b32 v[54:55], v119 offset0:128 offset1:160
	ds_read2_b32 v[56:57], v119 offset0:192 offset1:224
	ds_read2_b32 v[58:59], v120 offset1:32
	ds_read2_b32 v[60:61], v120 offset0:64 offset1:96
	ds_read2_b32 v[62:63], v120 offset0:128 offset1:160
	ds_read2_b32 v[64:65], v120 offset0:192 offset1:224
	ds_read2_b32 v[66:67], v121 offset1:32
	ds_read2_b32 v[68:69], v121 offset0:64 offset1:96
	ds_read2_b32 v[70:71], v121 offset0:128 offset1:160
	ds_read2_b32 v[72:73], v121 offset0:192 offset1:224
	s_lshr_b32 s46, s41, 6
	s_and_b32 s47, s41, 63
	s_lshl_b32 s36, s47, 19
	s_lshl_b32 s37, s46, 7
	s_add_i32 s36, s36, s37
	s_add_u32 s38, s28, s36
	s_addc_u32 s39, s29, 0
	s_waitcnt lgkmcnt(12)
	v_cvt_pk_bf16_f32 v94, v42, v43
	v_cvt_pk_bf16_f32 v95, v44, v45
	v_cvt_pk_bf16_f32 v96, v46, v47
	v_cvt_pk_bf16_f32 v97, v48, v49
	s_waitcnt lgkmcnt(8)
	v_cvt_pk_bf16_f32 v98, v50, v51
	v_cvt_pk_bf16_f32 v99, v52, v53
	v_cvt_pk_bf16_f32 v100, v54, v55
	v_cvt_pk_bf16_f32 v101, v56, v57
	s_waitcnt lgkmcnt(4)
	v_cvt_pk_bf16_f32 v102, v58, v59
	v_cvt_pk_bf16_f32 v103, v60, v61
	v_cvt_pk_bf16_f32 v104, v62, v63
	v_cvt_pk_bf16_f32 v105, v64, v65
	s_waitcnt lgkmcnt(0)
	v_cvt_pk_bf16_f32 v106, v66, v67
	v_cvt_pk_bf16_f32 v107, v68, v69
	v_cvt_pk_bf16_f32 v108, v70, v71
	v_cvt_pk_bf16_f32 v109, v72, v73
	global_store_dwordx4 v74, v[94:97], s[38:39] sc1
	global_store_dwordx4 v75, v[98:101], s[38:39] sc1
	global_store_dwordx4 v76, v[102:105], s[38:39] sc1
	global_store_dwordx4 v77, v[106:109], s[38:39] sc1
	s_waitcnt vmcnt(0) lgkmcnt(0)
